# stacked + accumulator clears of the GEMM units use v_mov_b64 (half the clear instructions)
# baseline (speedup 1.0000x reference)
.LBB0_119:
	s_ashr_i32 s21, s20, 31
	s_lshl_b64 s[26:27], s[20:21], 20
	s_add_u32 s26, s14, s26
	s_addc_u32 s27, s15, s27
	s_and_b64 s[28:29], s[28:29], exec
	s_cselect_b32 s21, s27, s43
	s_cselect_b32 s50, s26, s42
	s_add_u32 s40, s40, 0x80080
	s_addc_u32 s41, s41, 0
	s_add_u32 s51, s42, 0x100
	v_mov_b32_e32 v0, 0
	s_addc_u32 s52, s43, 0
	s_mov_b32 s53, -2
	s_waitcnt lgkmcnt(0)
	v_mov_b32_e32 v1, v0
	v_mov_b64_e32 v[2:3], 0
	v_mov_b64_e32 v[4:5], 0
	v_mov_b64_e32 v[6:7], 0
	v_mov_b64_e32 v[16:17], 0
	v_mov_b64_e32 v[18:19], 0
	v_mov_b64_e32 v[20:21], 0
	v_mov_b64_e32 v[22:23], 0
	s_waitcnt vmcnt(0)
	v_mov_b64_e32 v[34:35], 0
	v_mov_b64_e32 v[36:37], 0
	v_mov_b64_e32 v[38:39], 0
	v_mov_b64_e32 v[40:41], 0
	v_mov_b64_e32 v[50:51], 0
	v_mov_b64_e32 v[52:53], 0
	v_mov_b64_e32 v[54:55], 0
	v_mov_b64_e32 v[56:57], 0
	v_mov_b64_e32 v[8:9], 0
	v_mov_b64_e32 v[10:11], 0
	v_mov_b64_e32 v[12:13], 0
	v_mov_b64_e32 v[14:15], 0
	v_mov_b64_e32 v[24:25], 0
	v_mov_b64_e32 v[26:27], 0
	v_mov_b64_e32 v[28:29], 0
	v_mov_b64_e32 v[30:31], 0
	v_mov_b64_e32 v[42:43], 0
	v_mov_b64_e32 v[44:45], 0
	v_mov_b64_e32 v[46:47], 0
	v_mov_b64_e32 v[48:49], 0
	v_mov_b64_e32 v[58:59], 0
	v_mov_b64_e32 v[60:61], 0
	v_mov_b64_e32 v[62:63], 0
	v_mov_b64_e32 v[64:65], 0
	v_mov_b64_e32 v[66:67], 0
	v_mov_b64_e32 v[68:69], 0
	v_mov_b64_e32 v[70:71], 0
	v_mov_b64_e32 v[72:73], 0
	v_mov_b64_e32 v[82:83], 0
	v_mov_b64_e32 v[84:85], 0
	v_mov_b64_e32 v[86:87], 0
	v_mov_b64_e32 v[88:89], 0
	v_mov_b64_e32 v[98:99], 0
	v_mov_b64_e32 v[100:101], 0
	v_mov_b64_e32 v[102:103], 0
	v_mov_b64_e32 v[104:105], 0
	v_mov_b64_e32 v[114:115], 0
	v_mov_b64_e32 v[116:117], 0
	v_mov_b64_e32 v[118:119], 0
	v_mov_b64_e32 v[120:121], 0
	v_mov_b64_e32 v[74:75], 0
	v_mov_b64_e32 v[76:77], 0
	v_mov_b64_e32 v[78:79], 0
	v_mov_b64_e32 v[80:81], 0
	v_mov_b64_e32 v[90:91], 0
	v_mov_b64_e32 v[92:93], 0
	v_mov_b64_e32 v[94:95], 0
	v_mov_b64_e32 v[96:97], 0
	v_mov_b64_e32 v[106:107], 0
	v_mov_b64_e32 v[108:109], 0
	v_mov_b64_e32 v[110:111], 0
	v_mov_b64_e32 v[112:113], 0
	v_mov_b64_e32 v[122:123], 0
	v_mov_b64_e32 v[124:125], 0
	v_mov_b64_e32 v[126:127], 0
	v_mov_b64_e32 v[128:129], 0
	s_and_b64 vcc, exec, s[18:19]
	s_cbranch_vccnz .Lprio_skip_120
	s_setprio 1

.LBB0_679:
	v_mov_b32_e32 v0, 0
	s_mov_b32 s1, s49
	s_mov_b32 s12, s22
	v_mov_b32_e32 v1, v0
	v_mov_b64_e32 v[2:3], 0
	v_mov_b64_e32 v[4:5], 0
	v_mov_b64_e32 v[6:7], 0
	v_mov_b64_e32 v[8:9], 0
	v_mov_b64_e32 v[10:11], 0
	v_mov_b64_e32 v[12:13], 0
	v_mov_b64_e32 v[14:15], 0
	v_mov_b64_e32 v[16:17], 0
	v_mov_b64_e32 v[18:19], 0
	v_mov_b64_e32 v[20:21], 0
	v_mov_b64_e32 v[22:23], 0
	v_mov_b64_e32 v[24:25], 0
	v_mov_b64_e32 v[26:27], 0
	v_mov_b64_e32 v[28:29], 0
	v_mov_b64_e32 v[30:31], 0
	v_mov_b64_e32 v[34:35], 0
	v_mov_b64_e32 v[36:37], 0
	v_mov_b64_e32 v[38:39], 0
	v_mov_b64_e32 v[40:41], 0
	v_mov_b64_e32 v[42:43], 0
	v_mov_b64_e32 v[44:45], 0
	v_mov_b64_e32 v[46:47], 0
	v_mov_b64_e32 v[48:49], 0
	v_mov_b64_e32 v[50:51], 0
	v_mov_b64_e32 v[52:53], 0
	v_mov_b64_e32 v[54:55], 0
	v_mov_b64_e32 v[56:57], 0
	v_mov_b64_e32 v[58:59], 0
	v_mov_b64_e32 v[60:61], 0
	v_mov_b64_e32 v[62:63], 0
	v_mov_b64_e32 v[64:65], 0
	v_mov_b64_e32 v[66:67], 0
	v_mov_b64_e32 v[68:69], 0
	v_mov_b64_e32 v[70:71], 0
	v_mov_b64_e32 v[72:73], 0
	v_mov_b64_e32 v[74:75], 0
	v_mov_b64_e32 v[76:77], 0
	v_mov_b64_e32 v[78:79], 0
	v_mov_b64_e32 v[80:81], 0
	v_mov_b64_e32 v[82:83], 0
	v_mov_b64_e32 v[84:85], 0
	v_mov_b64_e32 v[86:87], 0
	v_mov_b64_e32 v[88:89], 0
	v_mov_b64_e32 v[90:91], 0
	v_mov_b64_e32 v[92:93], 0
	v_mov_b64_e32 v[94:95], 0
	v_mov_b64_e32 v[96:97], 0
	v_mov_b64_e32 v[98:99], 0
	v_mov_b64_e32 v[100:101], 0
	v_mov_b64_e32 v[102:103], 0
	v_mov_b64_e32 v[104:105], 0
	v_mov_b64_e32 v[106:107], 0
	v_mov_b64_e32 v[108:109], 0
	v_mov_b64_e32 v[110:111], 0
	v_mov_b64_e32 v[112:113], 0
	v_mov_b64_e32 v[114:115], 0
	v_mov_b64_e32 v[116:117], 0
	v_mov_b64_e32 v[118:119], 0
	v_mov_b64_e32 v[120:121], 0
	v_mov_b64_e32 v[122:123], 0
	v_mov_b64_e32 v[124:125], 0
	v_mov_b64_e32 v[126:127], 0
	v_mov_b64_e32 v[128:129], 0
	s_mov_b64 s[16:17], s[38:39]
	s_mov_b32 s50, s51
	s_andn2_b64 vcc, exec, s[26:27]
	s_mov_b64 s[40:41], s[30:31]
	s_cbranch_vccz .LBB0_708

.LBB0_754:
	s_add_u32 s33, s6, 0x100
	v_mov_b32_e32 v0, 0
	s_addc_u32 s50, s7, 0
	s_mov_b32 s51, -2
	s_waitcnt lgkmcnt(0)
	v_mov_b32_e32 v1, v0
	v_mov_b64_e32 v[2:3], 0
	v_mov_b64_e32 v[4:5], 0
	v_mov_b64_e32 v[6:7], 0
	v_mov_b64_e32 v[16:17], 0
	v_mov_b64_e32 v[18:19], 0
	v_mov_b64_e32 v[20:21], 0
	v_mov_b64_e32 v[22:23], 0
	s_waitcnt vmcnt(0)
	v_mov_b64_e32 v[34:35], 0
	v_mov_b64_e32 v[36:37], 0
	v_mov_b64_e32 v[38:39], 0
	v_mov_b64_e32 v[40:41], 0
	v_mov_b64_e32 v[50:51], 0
	v_mov_b64_e32 v[52:53], 0
	v_mov_b64_e32 v[54:55], 0
	v_mov_b64_e32 v[56:57], 0
	v_mov_b64_e32 v[8:9], 0
	v_mov_b64_e32 v[10:11], 0
	v_mov_b64_e32 v[12:13], 0
	v_mov_b64_e32 v[14:15], 0
	v_mov_b64_e32 v[24:25], 0
	v_mov_b64_e32 v[26:27], 0
	v_mov_b64_e32 v[28:29], 0
	v_mov_b64_e32 v[30:31], 0
	v_mov_b64_e32 v[42:43], 0
	v_mov_b64_e32 v[44:45], 0
	v_mov_b64_e32 v[46:47], 0
	v_mov_b64_e32 v[48:49], 0
	v_mov_b64_e32 v[58:59], 0
	v_mov_b64_e32 v[60:61], 0
	v_mov_b64_e32 v[62:63], 0
	v_mov_b64_e32 v[64:65], 0
	v_mov_b64_e32 v[66:67], 0
	v_mov_b64_e32 v[68:69], 0
	v_mov_b64_e32 v[70:71], 0
	v_mov_b64_e32 v[72:73], 0
	v_mov_b64_e32 v[82:83], 0
	v_mov_b64_e32 v[84:85], 0
	v_mov_b64_e32 v[86:87], 0
	v_mov_b64_e32 v[88:89], 0
	v_mov_b64_e32 v[98:99], 0
	v_mov_b64_e32 v[100:101], 0
	v_mov_b64_e32 v[102:103], 0
	v_mov_b64_e32 v[104:105], 0
	v_mov_b64_e32 v[114:115], 0
	v_mov_b64_e32 v[116:117], 0
	v_mov_b64_e32 v[118:119], 0
	v_mov_b64_e32 v[120:121], 0
	v_mov_b64_e32 v[74:75], 0
	v_mov_b64_e32 v[76:77], 0
	v_mov_b64_e32 v[78:79], 0
	v_mov_b64_e32 v[80:81], 0
	v_mov_b64_e32 v[90:91], 0
	v_mov_b64_e32 v[92:93], 0
	v_mov_b64_e32 v[94:95], 0
	v_mov_b64_e32 v[96:97], 0
	v_mov_b64_e32 v[106:107], 0
	v_mov_b64_e32 v[108:109], 0
	v_mov_b64_e32 v[110:111], 0
	v_mov_b64_e32 v[112:113], 0
	v_mov_b64_e32 v[122:123], 0
	v_mov_b64_e32 v[124:125], 0
	v_mov_b64_e32 v[126:127], 0
	v_mov_b64_e32 v[128:129], 0
	s_and_b64 vcc, exec, s[18:19]
	s_cbranch_vccnz .Lprio_skip_755
	s_setprio 1

.LBB0_882:
	v_mov_b32_e32 v0, 0
	s_mov_b32 s1, s47
	s_mov_b32 s12, s20
	v_mov_b32_e32 v1, v0
	v_mov_b64_e32 v[2:3], 0
	v_mov_b64_e32 v[4:5], 0
	v_mov_b64_e32 v[6:7], 0
	v_mov_b64_e32 v[8:9], 0
	v_mov_b64_e32 v[10:11], 0
	v_mov_b64_e32 v[12:13], 0
	v_mov_b64_e32 v[14:15], 0
	v_mov_b64_e32 v[16:17], 0
	v_mov_b64_e32 v[18:19], 0
	v_mov_b64_e32 v[20:21], 0
	v_mov_b64_e32 v[22:23], 0
	v_mov_b64_e32 v[24:25], 0
	v_mov_b64_e32 v[26:27], 0
	v_mov_b64_e32 v[28:29], 0
	v_mov_b64_e32 v[30:31], 0
	v_mov_b64_e32 v[34:35], 0
	v_mov_b64_e32 v[36:37], 0
	v_mov_b64_e32 v[38:39], 0
	v_mov_b64_e32 v[40:41], 0
	v_mov_b64_e32 v[42:43], 0
	v_mov_b64_e32 v[44:45], 0
	v_mov_b64_e32 v[46:47], 0
	v_mov_b64_e32 v[48:49], 0
	v_mov_b64_e32 v[50:51], 0
	v_mov_b64_e32 v[52:53], 0
	v_mov_b64_e32 v[54:55], 0
	v_mov_b64_e32 v[56:57], 0
	v_mov_b64_e32 v[58:59], 0
	v_mov_b64_e32 v[60:61], 0
	v_mov_b64_e32 v[62:63], 0
	v_mov_b64_e32 v[64:65], 0
	v_mov_b64_e32 v[66:67], 0
	v_mov_b64_e32 v[68:69], 0
	v_mov_b64_e32 v[70:71], 0
	v_mov_b64_e32 v[72:73], 0
	v_mov_b64_e32 v[74:75], 0
	v_mov_b64_e32 v[76:77], 0
	v_mov_b64_e32 v[78:79], 0
	v_mov_b64_e32 v[80:81], 0
	v_mov_b64_e32 v[82:83], 0
	v_mov_b64_e32 v[84:85], 0
	v_mov_b64_e32 v[86:87], 0
	v_mov_b64_e32 v[88:89], 0
	v_mov_b64_e32 v[90:91], 0
	v_mov_b64_e32 v[92:93], 0
	v_mov_b64_e32 v[94:95], 0
	v_mov_b64_e32 v[96:97], 0
	v_mov_b64_e32 v[98:99], 0
	v_mov_b64_e32 v[100:101], 0
	v_mov_b64_e32 v[102:103], 0
	v_mov_b64_e32 v[104:105], 0
	v_mov_b64_e32 v[106:107], 0
	v_mov_b64_e32 v[108:109], 0
	v_mov_b64_e32 v[110:111], 0
	v_mov_b64_e32 v[112:113], 0
	v_mov_b64_e32 v[114:115], 0
	v_mov_b64_e32 v[116:117], 0
	v_mov_b64_e32 v[118:119], 0
	v_mov_b64_e32 v[120:121], 0
	v_mov_b64_e32 v[122:123], 0
	v_mov_b64_e32 v[124:125], 0
	v_mov_b64_e32 v[126:127], 0
	v_mov_b64_e32 v[128:129], 0
	s_mov_b64 s[16:17], s[28:29]
	s_mov_b32 s48, s49
	s_andn2_b64 vcc, exec, s[22:23]
	s_mov_b64 s[30:31], s[26:27]
	s_cbranch_vccz .LBB0_895
